# LN-phase wave sums (7 sites): 6-step ds_bpermute xor butterflies replaced by DPP quad_perm/row_half_mirror/row_mirror adds + permlane16/32 swaps, same pairing and association (bit-identical)
# baseline (speedup 1.0000x reference)
.LBB0_924:
	v_lshl_add_u64 v[18:19], s[72:73], 0, v[122:123]
	v_add_co_u32_e32 v14, vcc, 0x1ab00000, v18
	s_nop 1
	v_addc_co_u32_e32 v15, vcc, 0, v19, vcc
	global_load_dwordx4 v[6:9], v[14:15], off offset:1024
	global_load_dwordx4 v[2:5], v[14:15], off
	global_load_dwordx4 v[10:13], v[14:15], off offset:2048
	s_nop 0
	global_load_dwordx4 v[14:17], v[14:15], off offset:3072
	v_add_co_u32_e32 v30, vcc, 0x1ab01000, v18
	s_nop 1
	v_addc_co_u32_e32 v31, vcc, 0, v19, vcc
	global_load_dwordx4 v[18:21], v[30:31], off
	global_load_dwordx4 v[22:25], v[30:31], off offset:1024
	global_load_dwordx4 v[26:29], v[30:31], off offset:2048
	s_nop 0
	global_load_dwordx4 v[30:33], v[30:31], off offset:3072
	s_waitcnt vmcnt(4)
	v_mov_b32_e32 v36, v6
	v_mov_b32_e32 v37, v2
	v_mov_b32_e32 v38, v7
	v_mov_b32_e32 v39, v3
	v_mov_b32_e32 v40, v8
	v_mov_b32_e32 v41, v4
	v_mov_b32_e32 v42, v9
	v_mov_b32_e32 v43, v5
	v_mov_b32_e32 v44, v11
	v_mov_b32_e32 v45, v12
	v_mov_b32_e32 v46, v10
	v_mov_b32_e32 v47, v13
	v_pk_add_f32 v[36:37], v[36:37], v[38:39]
	v_pk_add_f32 v[38:39], v[40:41], v[42:43]
	v_pk_add_f32 v[40:41], v[44:45], v[46:47]
	v_pk_add_f32 v[36:37], v[36:37], v[38:39]
	v_pk_add_f32 v[38:39], v[40:41], v[40:41] op_sel_hi:[0,1]
	v_add_f32_e32 v34, 0, v37
	v_add_f32_e32 v49, v14, v15
	v_add_f32_e32 v51, v16, v17
	v_add_f32_e32 v43, v36, v34
	s_waitcnt vmcnt(3)
	v_mov_b32_e32 v48, v18
	v_mov_b32_e32 v50, v19
	v_mov_b32_e32 v42, v21
	v_mov_b32_e32 v38, v20
	s_waitcnt vmcnt(2)
	v_mov_b32_e32 v44, v23
	v_mov_b32_e32 v45, v24
	v_mov_b32_e32 v46, v22
	v_mov_b32_e32 v47, v25
	v_pk_add_f32 v[40:41], v[48:49], v[50:51]
	v_pk_add_f32 v[36:37], v[38:39], v[42:43]
	v_pk_add_f32 v[44:45], v[44:45], v[46:47]
	v_pk_add_f32 v[36:37], v[40:41], v[36:37]
	v_pk_add_f32 v[44:45], v[44:45], v[44:45] op_sel_hi:[0,1]
	v_pk_add_f32 v[36:37], v[36:37], v[36:37] op_sel_hi:[0,1]
	s_waitcnt vmcnt(1)
	v_add_f32_e32 v53, v26, v27
	v_add_f32_e32 v55, v28, v29
	s_waitcnt vmcnt(0)
	v_mov_b32_e32 v52, v30
	v_mov_b32_e32 v54, v31
	v_mov_b32_e32 v44, v32
	v_mov_b32_e32 v36, v33
	v_pk_add_f32 v[46:47], v[52:53], v[54:55]
	v_pk_add_f32 v[36:37], v[44:45], v[36:37]
	s_nop 0
	v_pk_add_f32 v[36:37], v[46:47], v[36:37]
	s_nop 0
	v_add_f32_e32 v34, v36, v37
	s_waitcnt lgkmcnt(0)
	s_nop 1
	v_add_f32_dpp v34, v34, v34 quad_perm:[1,0,3,2] row_mask:0xf bank_mask:0xf
	s_nop 1
	v_add_f32_dpp v34, v34, v34 quad_perm:[2,3,0,1] row_mask:0xf bank_mask:0xf
	s_nop 1
	v_add_f32_dpp v34, v34, v34 row_half_mirror row_mask:0xf bank_mask:0xf
	s_nop 1
	v_add_f32_dpp v34, v34, v34 row_mirror row_mask:0xf bank_mask:0xf
	v_mov_b32_e32 v36, v34
	s_nop 1
	v_permlane16_swap_b32_e32 v34, v36
	v_add_f32_e32 v34, v34, v36
	v_mov_b32_e32 v36, v34
	s_nop 1
	v_permlane32_swap_b32_e32 v34, v36
	v_add_f32_e32 v121, v34, v36
	v_fmamk_f32 v126, v121, 0xba000000, v5
	v_fmamk_f32 v128, v121, 0xba000000, v4
	v_fmamk_f32 v4, v121, 0xba000000, v3
	v_fmamk_f32 v127, v121, 0xba000000, v9
	v_fmamk_f32 v5, v121, 0xba000000, v7
	v_fmac_f32_e32 v6, 0xba000000, v121
	v_fmamk_f32 v13, v121, 0xba000000, v13
	v_fmamk_f32 v12, v121, 0xba000000, v12
	v_fmamk_f32 v11, v121, 0xba000000, v11
	v_fmac_f32_e32 v10, 0xba000000, v121
	v_fmac_f32_e32 v2, 0xba000000, v121
	v_fmamk_f32 v129, v121, 0xba000000, v8
	v_mov_b32_e32 v3, v6
	v_pk_mul_f32 v[8:9], v[4:5], v[4:5]
	v_pk_mul_f32 v[36:37], v[126:127], v[126:127]
	v_pk_mul_f32 v[38:39], v[12:13], v[12:13]
	v_pk_mul_f32 v[40:41], v[10:11], v[10:11]
	v_fmamk_f32 v16, v121, 0xba000000, v16
	v_fmac_f32_e32 v14, 0xba000000, v121
	v_pk_fma_f32 v[8:9], v[2:3], v[2:3], v[8:9]
	v_pk_fma_f32 v[36:37], v[128:129], v[128:129], v[36:37]
	v_pk_mov_b32 v[52:53], v[40:41], v[38:39] op_sel:[1,0]
	v_mov_b32_e32 v41, v39
	v_fmamk_f32 v17, v121, 0xba000000, v17
	v_fmamk_f32 v15, v121, 0xba000000, v15
	v_fmamk_f32 v25, v121, 0xba000000, v25
	v_fmamk_f32 v24, v121, 0xba000000, v24
	v_fmamk_f32 v23, v121, 0xba000000, v23
	v_fmac_f32_e32 v22, 0xba000000, v121
	v_mul_f32_e32 v34, v14, v14
	v_mul_f32_e32 v42, v16, v16
	v_pk_add_f32 v[8:9], v[8:9], v[36:37]
	v_pk_add_f32 v[36:37], v[52:53], v[40:41]
	v_fmamk_f32 v21, v121, 0xba000000, v21
	v_fmamk_f32 v20, v121, 0xba000000, v20
	v_fmamk_f32 v19, v121, 0xba000000, v19
	v_fmac_f32_e32 v18, 0xba000000, v121
	v_pk_mul_f32 v[44:45], v[24:25], v[24:25]
	v_pk_mul_f32 v[46:47], v[22:23], v[22:23]
	v_pk_fma_f32 v[38:39], v[14:15], v[14:15], v[34:35] op_sel_hi:[1,1,0]
	v_pk_fma_f32 v[42:43], v[16:17], v[16:17], v[42:43] op_sel_hi:[1,1,0]
	v_pk_add_f32 v[8:9], v[8:9], v[8:9] op_sel_hi:[0,1]
	v_pk_add_f32 v[36:37], v[36:37], v[36:37] op_sel_hi:[0,1]
	v_fmamk_f32 v28, v121, 0xba000000, v28
	v_fmac_f32_e32 v26, 0xba000000, v121
	v_pk_mov_b32 v[54:55], v[46:47], v[44:45] op_sel:[1,0]
	v_mov_b32_e32 v47, v45
	v_mul_f32_e32 v38, v18, v18
	v_mul_f32_e32 v42, v19, v19
	v_mul_f32_e32 v36, v20, v20
	v_mul_f32_e32 v8, v21, v21
	v_fmamk_f32 v29, v121, 0xba000000, v29
	v_fmamk_f32 v27, v121, 0xba000000, v27
	v_mul_f32_e32 v48, v26, v26
	v_mul_f32_e32 v50, v28, v28
	v_pk_add_f32 v[40:41], v[54:55], v[46:47]
	v_pk_add_f32 v[38:39], v[38:39], v[42:43]
	v_pk_add_f32 v[8:9], v[36:37], v[8:9]
	v_pk_fma_f32 v[138:139], v[26:27], v[26:27], v[48:49] op_sel_hi:[1,1,0]
	v_pk_fma_f32 v[140:141], v[28:29], v[28:29], v[50:51] op_sel_hi:[1,1,0]
	v_pk_add_f32 v[142:143], v[40:41], v[40:41] op_sel_hi:[0,1]
	v_pk_add_f32 v[8:9], v[38:39], v[8:9]
	global_load_dwordx4 v[92:95], v[100:101], off
	global_load_dwordx4 v[84:87], v[100:101], off offset:1024
	global_load_dwordx4 v[96:99], v[102:103], off
	global_load_dwordx4 v[88:91], v[102:103], off offset:1024
	global_load_dwordx4 v[76:79], v[100:101], off offset:2048
	global_load_dwordx4 v[68:71], v[100:101], off offset:3072
	global_load_dwordx4 v[80:83], v[102:103], off offset:2048
	global_load_dwordx4 v[72:75], v[102:103], off offset:3072
	global_load_dwordx4 v[60:63], v[104:105], off
	global_load_dwordx4 v[64:67], v[106:107], off
	global_load_dwordx4 v[52:55], v[108:109], off
	global_load_dwordx4 v[56:59], v[110:111], off
	global_load_dwordx4 v[44:47], v[112:113], off
	global_load_dwordx4 v[48:51], v[114:115], off
	global_load_dwordx4 v[36:39], v[116:117], off
	global_load_dwordx4 v[40:43], v[118:119], off
	v_fmamk_f32 v33, v121, 0xba000000, v33
	v_pk_add_f32 v[8:9], v[8:9], v[8:9] op_sel_hi:[0,1]
	v_fmamk_f32 v32, v121, 0xba000000, v32
	v_fmamk_f32 v31, v121, 0xba000000, v31
	v_fmac_f32_e32 v30, 0xba000000, v121
	v_mul_f32_e32 v138, v30, v30
	v_mul_f32_e32 v140, v31, v31
	v_mul_f32_e32 v142, v32, v32
	v_mul_f32_e32 v8, v33, v33
	v_pk_add_f32 v[138:139], v[138:139], v[140:141]
	v_pk_add_f32 v[8:9], v[142:143], v[8:9]
	s_nop 0
	v_pk_add_f32 v[8:9], v[138:139], v[8:9]
	s_nop 0
	v_add_f32_e32 v3, v8, v9
	s_waitcnt lgkmcnt(0)
	s_nop 1
	v_add_f32_dpp v3, v3, v3 quad_perm:[1,0,3,2] row_mask:0xf bank_mask:0xf
	s_nop 1
	v_add_f32_dpp v3, v3, v3 quad_perm:[2,3,0,1] row_mask:0xf bank_mask:0xf
	s_nop 1
	v_add_f32_dpp v3, v3, v3 row_half_mirror row_mask:0xf bank_mask:0xf
	s_nop 1
	v_add_f32_dpp v3, v3, v3 row_mirror row_mask:0xf bank_mask:0xf
	v_mov_b32_e32 v7, v3
	s_nop 1
	v_permlane16_swap_b32_e32 v3, v7
	v_add_f32_e32 v3, v3, v7
	v_mov_b32_e32 v7, v3
	s_nop 1
	v_permlane32_swap_b32_e32 v3, v7
	v_add_f32_e32 v3, v3, v7
	v_fmamk_f32 v3, v3, 0x3a000000, v136
	v_mul_f32_e32 v7, 0x4f800000, v3
	v_cmp_gt_f32_e32 vcc, s1, v3
	s_nop 1
	v_cndmask_b32_e32 v3, v3, v7, vcc
	v_sqrt_f32_e32 v7, v3
	s_nop 0
	v_add_u32_e32 v8, -1, v7
	v_add_u32_e32 v9, 1, v7
	v_fma_f32 v34, -v8, v7, v3
	v_fma_f32 v138, -v9, v7, v3
	v_cmp_ge_f32_e64 s[8:9], 0, v34
	s_nop 1
	v_cndmask_b32_e64 v7, v7, v8, s[8:9]
	v_cmp_lt_f32_e64 s[8:9], 0, v138
	s_nop 1
	v_cndmask_b32_e64 v7, v7, v9, s[8:9]
	v_mul_f32_e32 v8, 0x37800000, v7
	v_cndmask_b32_e32 v7, v7, v8, vcc
	v_cmp_class_f32_e32 vcc, v3, v137
	s_nop 1
	v_cndmask_b32_e32 v3, v7, v3, vcc
	v_div_scale_f32 v7, s[4:5], v3, v3, 1.0
	v_rcp_f32_e32 v8, v7
	s_nop 0
	v_fma_f32 v9, -v7, v8, 1.0
	v_fmac_f32_e32 v8, v9, v8
	v_div_scale_f32 v9, vcc, 1.0, v3, 1.0
	v_mul_f32_e32 v34, v9, v8
	v_fma_f32 v138, -v7, v34, v9
	v_fmac_f32_e32 v34, v138, v8
	v_fma_f32 v7, -v7, v34, v9
	v_div_fmas_f32 v7, v7, v8, v34
	v_div_fixup_f32 v34, v7, v3, 1.0
	s_and_saveexec_b64 s[4:5], s[6:7]
	s_cbranch_execz .LBB0_923
	v_mul_f32_e32 v8, 0x3a000000, v121
	v_ashrrev_i32_e32 v121, 31, v120
	v_lshl_add_u64 v[138:139], v[120:121], 2, s[14:15]
	v_mov_b32_e32 v9, v34
	global_store_dwordx2 v[138:139], v[8:9], off
	s_branch .LBB0_923

.LBB0_1139:
	v_lshl_add_u64 v[2:3], s[72:73], 0, v[120:121]
	v_add_co_u32_e32 v4, vcc, 0x1ab00000, v2
	s_nop 1
	v_addc_co_u32_e32 v5, vcc, 0, v3, vcc
	global_load_dwordx4 v[30:33], v[4:5], off
	global_load_dwordx4 v[26:29], v[4:5], off offset:1024
	global_load_dwordx4 v[22:25], v[4:5], off offset:2048
	global_load_dwordx4 v[18:21], v[4:5], off offset:3072
	v_add_co_u32_e32 v2, vcc, 0x1ab01000, v2
	s_nop 1
	v_addc_co_u32_e32 v3, vcc, 0, v3, vcc
	global_load_dwordx4 v[14:17], v[2:3], off
	global_load_dwordx4 v[10:13], v[2:3], off offset:1024
	global_load_dwordx4 v[6:9], v[2:3], off offset:2048
	s_nop 0
	global_load_dwordx4 v[2:5], v[2:3], off offset:3072
	s_waitcnt vmcnt(4)
	v_mov_b32_e32 v34, v30
	v_mov_b32_e32 v35, v26
	v_mov_b32_e32 v36, v31
	v_mov_b32_e32 v37, v27
	v_mov_b32_e32 v38, v32
	v_mov_b32_e32 v39, v28
	v_mov_b32_e32 v40, v33
	v_mov_b32_e32 v41, v29
	v_mov_b32_e32 v42, v23
	v_mov_b32_e32 v43, v24
	v_mov_b32_e32 v44, v22
	v_mov_b32_e32 v45, v25
	v_pk_add_f32 v[34:35], v[34:35], v[36:37]
	v_pk_add_f32 v[36:37], v[38:39], v[40:41]
	v_pk_add_f32 v[38:39], v[42:43], v[44:45]
	v_pk_add_f32 v[34:35], v[34:35], v[36:37]
	v_pk_add_f32 v[36:37], v[38:39], v[38:39] op_sel:[0,1] op_sel_hi:[1,0]
	v_add_f32_e32 v34, 0, v34
	v_add_f32_e32 v46, v18, v19
	v_add_f32_e32 v48, v20, v21
	v_add_f32_e32 v40, v34, v35
	s_waitcnt vmcnt(3)
	v_mov_b32_e32 v41, v14
	v_mov_b32_e32 v47, v16
	v_mov_b32_e32 v49, v17
	v_mov_b32_e32 v37, v15
	s_waitcnt vmcnt(2)
	v_mov_b32_e32 v42, v11
	v_mov_b32_e32 v43, v12
	v_mov_b32_e32 v44, v10
	v_mov_b32_e32 v45, v13
	v_pk_add_f32 v[38:39], v[46:47], v[48:49]
	v_pk_add_f32 v[34:35], v[40:41], v[36:37]
	v_pk_add_f32 v[42:43], v[42:43], v[44:45]
	v_pk_add_f32 v[34:35], v[34:35], v[38:39]
	v_pk_add_f32 v[42:43], v[42:43], v[42:43] op_sel:[0,1] op_sel_hi:[1,0]
	v_pk_add_f32 v[34:35], v[34:35], v[34:35] op_sel:[0,1] op_sel_hi:[1,0]
	s_waitcnt vmcnt(1)
	v_add_f32_e32 v50, v6, v7
	v_add_f32_e32 v52, v8, v9
	s_waitcnt vmcnt(0)
	v_mov_b32_e32 v51, v4
	v_mov_b32_e32 v53, v5
	v_mov_b32_e32 v43, v3
	v_mov_b32_e32 v35, v2
	v_pk_add_f32 v[44:45], v[50:51], v[52:53]
	v_pk_add_f32 v[34:35], v[34:35], v[42:43]
	s_nop 0
	v_pk_add_f32 v[34:35], v[34:35], v[44:45]
	s_nop 0
	v_add_f32_e32 v34, v34, v35
	s_waitcnt lgkmcnt(0)
	s_nop 1
	v_add_f32_dpp v34, v34, v34 quad_perm:[1,0,3,2] row_mask:0xf bank_mask:0xf
	s_nop 1
	v_add_f32_dpp v34, v34, v34 quad_perm:[2,3,0,1] row_mask:0xf bank_mask:0xf
	s_nop 1
	v_add_f32_dpp v34, v34, v34 row_half_mirror row_mask:0xf bank_mask:0xf
	s_nop 1
	v_add_f32_dpp v34, v34, v34 row_mirror row_mask:0xf bank_mask:0xf
	v_mov_b32_e32 v35, v34
	s_nop 1
	v_permlane16_swap_b32_e32 v34, v35
	v_add_f32_e32 v34, v34, v35
	v_mov_b32_e32 v35, v34
	s_nop 1
	v_permlane32_swap_b32_e32 v34, v35
	v_add_f32_e32 v119, v34, v35
	v_fmamk_f32 v124, v119, 0xba000000, v33
	v_fmamk_f32 v128, v119, 0xba000000, v31
	v_fmamk_f32 v125, v119, 0xba000000, v29
	v_fmamk_f32 v129, v119, 0xba000000, v27
	v_fmac_f32_e32 v26, 0xba000000, v119
	v_fmamk_f32 v25, v119, 0xba000000, v25
	v_fmamk_f32 v24, v119, 0xba000000, v24
	v_fmamk_f32 v23, v119, 0xba000000, v23
	v_fmac_f32_e32 v22, 0xba000000, v119
	v_fmamk_f32 v126, v119, 0xba000000, v32
	v_fmac_f32_e32 v30, 0xba000000, v119
	v_fmamk_f32 v127, v119, 0xba000000, v28
	v_mov_b32_e32 v31, v26
	v_pk_mul_f32 v[28:29], v[128:129], v[128:129]
	v_pk_mul_f32 v[32:33], v[124:125], v[124:125]
	v_pk_mul_f32 v[34:35], v[24:25], v[24:25]
	v_pk_mul_f32 v[36:37], v[22:23], v[22:23]
	v_fmamk_f32 v20, v119, 0xba000000, v20
	v_fmac_f32_e32 v18, 0xba000000, v119
	v_pk_fma_f32 v[28:29], v[30:31], v[30:31], v[28:29]
	v_pk_fma_f32 v[32:33], v[126:127], v[126:127], v[32:33]
	v_pk_mov_b32 v[50:51], v[36:37], v[34:35] op_sel:[1,0]
	v_mov_b32_e32 v37, v35
	v_fmamk_f32 v21, v119, 0xba000000, v21
	v_fmamk_f32 v19, v119, 0xba000000, v19
	v_fmamk_f32 v13, v119, 0xba000000, v13
	v_fmamk_f32 v12, v119, 0xba000000, v12
	v_fmamk_f32 v11, v119, 0xba000000, v11
	v_fmac_f32_e32 v10, 0xba000000, v119
	v_mul_f32_e32 v38, v18, v18
	v_mul_f32_e32 v40, v20, v20
	v_pk_add_f32 v[28:29], v[28:29], v[32:33]
	v_pk_add_f32 v[32:33], v[50:51], v[36:37]
	v_fmamk_f32 v17, v119, 0xba000000, v17
	v_fmamk_f32 v16, v119, 0xba000000, v16
	v_fmamk_f32 v15, v119, 0xba000000, v15
	v_fmac_f32_e32 v14, 0xba000000, v119
	v_pk_mul_f32 v[42:43], v[12:13], v[12:13]
	v_pk_mul_f32 v[44:45], v[10:11], v[10:11]
	v_pk_fma_f32 v[34:35], v[18:19], v[18:19], v[38:39] op_sel_hi:[1,1,0]
	v_pk_fma_f32 v[38:39], v[20:21], v[20:21], v[40:41] op_sel_hi:[1,1,0]
	v_pk_add_f32 v[28:29], v[28:29], v[28:29] op_sel_hi:[0,1]
	v_pk_add_f32 v[32:33], v[32:33], v[32:33] op_sel_hi:[0,1]
	v_fmamk_f32 v8, v119, 0xba000000, v8
	v_fmac_f32_e32 v6, 0xba000000, v119
	v_pk_mov_b32 v[40:41], v[44:45], v[42:43] op_sel:[1,0]
	v_mov_b32_e32 v45, v43
	v_mul_f32_e32 v34, v14, v14
	v_mul_f32_e32 v38, v15, v15
	v_mul_f32_e32 v32, v16, v16
	v_mul_f32_e32 v28, v17, v17
	v_fmamk_f32 v9, v119, 0xba000000, v9
	v_fmamk_f32 v7, v119, 0xba000000, v7
	v_mul_f32_e32 v46, v6, v6
	v_mul_f32_e32 v48, v8, v8
	v_pk_add_f32 v[36:37], v[40:41], v[44:45]
	v_pk_add_f32 v[34:35], v[34:35], v[38:39]
	v_pk_add_f32 v[28:29], v[32:33], v[28:29]
	v_pk_fma_f32 v[136:137], v[6:7], v[6:7], v[46:47] op_sel_hi:[1,1,0]
	v_pk_fma_f32 v[138:139], v[8:9], v[8:9], v[48:49] op_sel_hi:[1,1,0]
	v_pk_add_f32 v[140:141], v[36:37], v[36:37] op_sel_hi:[0,1]
	v_pk_add_f32 v[28:29], v[34:35], v[28:29]
	global_load_dwordx4 v[88:91], v[98:99], off
	global_load_dwordx4 v[80:83], v[98:99], off offset:1024
	global_load_dwordx4 v[92:95], v[100:101], off
	global_load_dwordx4 v[84:87], v[100:101], off offset:1024
	global_load_dwordx4 v[72:75], v[98:99], off offset:2048
	global_load_dwordx4 v[64:67], v[98:99], off offset:3072
	global_load_dwordx4 v[76:79], v[100:101], off offset:2048
	global_load_dwordx4 v[68:71], v[100:101], off offset:3072
	global_load_dwordx4 v[56:59], v[102:103], off
	global_load_dwordx4 v[60:63], v[104:105], off
	global_load_dwordx4 v[48:51], v[106:107], off
	global_load_dwordx4 v[52:55], v[108:109], off
	global_load_dwordx4 v[40:43], v[110:111], off
	global_load_dwordx4 v[44:47], v[112:113], off
	global_load_dwordx4 v[32:35], v[114:115], off
	global_load_dwordx4 v[36:39], v[116:117], off
	v_fmamk_f32 v5, v119, 0xba000000, v5
	v_pk_add_f32 v[28:29], v[28:29], v[28:29] op_sel_hi:[0,1]
	v_fmamk_f32 v4, v119, 0xba000000, v4
	v_fmamk_f32 v3, v119, 0xba000000, v3
	v_fmac_f32_e32 v2, 0xba000000, v119
	v_mul_f32_e32 v136, v2, v2
	v_mul_f32_e32 v138, v3, v3
	v_mul_f32_e32 v140, v4, v4
	v_mul_f32_e32 v28, v5, v5
	v_pk_add_f32 v[136:137], v[136:137], v[138:139]
	v_pk_add_f32 v[28:29], v[140:141], v[28:29]
	s_nop 0
	v_pk_add_f32 v[28:29], v[136:137], v[28:29]
	s_nop 0
	v_add_f32_e32 v27, v28, v29
	s_waitcnt lgkmcnt(0)
	s_nop 1
	v_add_f32_dpp v27, v27, v27 quad_perm:[1,0,3,2] row_mask:0xf bank_mask:0xf
	s_nop 1
	v_add_f32_dpp v27, v27, v27 quad_perm:[2,3,0,1] row_mask:0xf bank_mask:0xf
	s_nop 1
	v_add_f32_dpp v27, v27, v27 row_half_mirror row_mask:0xf bank_mask:0xf
	s_nop 1
	v_add_f32_dpp v27, v27, v27 row_mirror row_mask:0xf bank_mask:0xf
	v_mov_b32_e32 v28, v27
	s_nop 1
	v_permlane16_swap_b32_e32 v27, v28
	v_add_f32_e32 v27, v27, v28
	v_mov_b32_e32 v28, v27
	s_nop 1
	v_permlane32_swap_b32_e32 v27, v28
	v_add_f32_e32 v27, v27, v28
	v_fmamk_f32 v27, v27, 0x3a000000, v97
	v_mul_f32_e32 v28, 0x4f800000, v27
	v_cmp_gt_f32_e32 vcc, s1, v27
	s_nop 1
	v_cndmask_b32_e32 v27, v27, v28, vcc
	v_sqrt_f32_e32 v28, v27
	s_nop 0
	v_add_u32_e32 v29, -1, v28
	v_add_u32_e32 v31, 1, v28
	v_fma_f32 v136, -v29, v28, v27
	v_fma_f32 v137, -v31, v28, v27
	v_cmp_ge_f32_e64 s[8:9], 0, v136
	s_nop 1
	v_cndmask_b32_e64 v28, v28, v29, s[8:9]
	v_cmp_lt_f32_e64 s[8:9], 0, v137
	s_nop 1
	v_cndmask_b32_e64 v28, v28, v31, s[8:9]
	v_mul_f32_e32 v29, 0x37800000, v28
	v_cndmask_b32_e32 v28, v28, v29, vcc
	v_cmp_class_f32_e32 vcc, v27, v135
	s_nop 1
	v_cndmask_b32_e32 v27, v28, v27, vcc
	v_div_scale_f32 v28, s[4:5], v27, v27, 1.0
	v_rcp_f32_e32 v29, v28
	s_nop 0
	v_fma_f32 v31, -v28, v29, 1.0
	v_fmac_f32_e32 v29, v31, v29
	v_div_scale_f32 v31, vcc, 1.0, v27, 1.0
	v_mul_f32_e32 v136, v31, v29
	v_fma_f32 v137, -v28, v136, v31
	v_fmac_f32_e32 v136, v137, v29
	v_fma_f32 v28, -v28, v136, v31
	v_div_fmas_f32 v28, v28, v29, v136
	v_div_fixup_f32 v28, v28, v27, 1.0
	s_and_saveexec_b64 s[4:5], s[6:7]
	s_cbranch_execz .LBB0_1138
	v_mul_f32_e32 v136, 0x3a000000, v119
	v_ashrrev_i32_e32 v119, 31, v118
	v_lshl_add_u64 v[138:139], v[118:119], 2, s[16:17]
	v_mov_b32_e32 v137, v28
	global_store_dwordx2 v[138:139], v[136:137], off
	s_branch .LBB0_1138

.LBB0_1962:
	v_lshl_add_u64 v[2:3], s[72:73], 0, v[128:129]
	v_add_co_u32_e32 v4, vcc, 0x1ab00000, v2
	s_nop 1
	v_addc_co_u32_e32 v5, vcc, 0, v3, vcc
	global_load_dwordx4 v[22:25], v[4:5], off offset:1024
	global_load_dwordx4 v[18:21], v[4:5], off
	global_load_dwordx4 v[26:29], v[4:5], off offset:2048
	global_load_dwordx4 v[30:33], v[4:5], off offset:3072
	v_add_co_u32_e32 v34, vcc, 0x1ab01000, v2
	s_waitcnt vmcnt(3)
	v_mov_b32_e32 v36, v23
	v_addc_co_u32_e32 v35, vcc, 0, v3, vcc
	global_load_dwordx4 v[2:5], v[34:35], off
	global_load_dwordx4 v[6:9], v[34:35], off offset:1024
	s_waitcnt lgkmcnt(2)
	global_load_dwordx4 v[10:13], v[34:35], off offset:2048
	s_waitcnt lgkmcnt(0)
	global_load_dwordx4 v[14:17], v[34:35], off offset:3072
	v_mov_b32_e32 v34, v22
	s_waitcnt vmcnt(6)
	v_mov_b32_e32 v35, v18
	v_mov_b32_e32 v37, v19
	v_mov_b32_e32 v38, v24
	v_mov_b32_e32 v39, v20
	v_mov_b32_e32 v42, v25
	v_mov_b32_e32 v43, v21
	s_waitcnt vmcnt(5)
	v_mov_b32_e32 v44, v27
	v_mov_b32_e32 v45, v28
	v_mov_b32_e32 v46, v26
	v_mov_b32_e32 v47, v29
	v_pk_add_f32 v[34:35], v[34:35], v[36:37]
	v_pk_add_f32 v[36:37], v[38:39], v[42:43]
	v_pk_add_f32 v[38:39], v[44:45], v[46:47]
	v_pk_add_f32 v[34:35], v[34:35], v[36:37]
	v_pk_add_f32 v[36:37], v[38:39], v[38:39] op_sel_hi:[0,1]
	v_add_f32_e32 v35, 0, v35
	s_waitcnt vmcnt(4)
	v_add_f32_e32 v49, v30, v31
	v_add_f32_e32 v51, v32, v33
	v_add_f32_e32 v43, v34, v35
	s_waitcnt vmcnt(3)
	v_mov_b32_e32 v48, v2
	v_mov_b32_e32 v50, v3
	v_mov_b32_e32 v42, v5
	v_mov_b32_e32 v36, v4
	s_waitcnt vmcnt(2)
	v_mov_b32_e32 v44, v7
	v_mov_b32_e32 v45, v8
	v_mov_b32_e32 v46, v6
	v_mov_b32_e32 v47, v9
	v_pk_add_f32 v[38:39], v[48:49], v[50:51]
	v_pk_add_f32 v[34:35], v[36:37], v[42:43]
	v_pk_add_f32 v[44:45], v[44:45], v[46:47]
	v_pk_add_f32 v[34:35], v[38:39], v[34:35]
	v_pk_add_f32 v[44:45], v[44:45], v[44:45] op_sel_hi:[0,1]
	v_pk_add_f32 v[34:35], v[34:35], v[34:35] op_sel_hi:[0,1]
	s_waitcnt vmcnt(1)
	v_add_f32_e32 v53, v10, v11
	v_add_f32_e32 v55, v12, v13
	s_waitcnt vmcnt(0)
	v_mov_b32_e32 v52, v14
	v_mov_b32_e32 v54, v15
	v_mov_b32_e32 v44, v16
	v_mov_b32_e32 v34, v17
	v_pk_add_f32 v[46:47], v[52:53], v[54:55]
	v_pk_add_f32 v[34:35], v[44:45], v[34:35]
	s_nop 0
	v_pk_add_f32 v[34:35], v[46:47], v[34:35]
	s_nop 0
	v_add_f32_e32 v34, v34, v35
	s_waitcnt lgkmcnt(0)
	s_nop 1
	v_add_f32_dpp v34, v34, v34 quad_perm:[1,0,3,2] row_mask:0xf bank_mask:0xf
	s_nop 1
	v_add_f32_dpp v34, v34, v34 quad_perm:[2,3,0,1] row_mask:0xf bank_mask:0xf
	s_nop 1
	v_add_f32_dpp v34, v34, v34 row_half_mirror row_mask:0xf bank_mask:0xf
	s_nop 1
	v_add_f32_dpp v34, v34, v34 row_mirror row_mask:0xf bank_mask:0xf
	v_mov_b32_e32 v35, v34
	s_nop 1
	v_permlane16_swap_b32_e32 v34, v35
	v_add_f32_e32 v34, v34, v35
	v_mov_b32_e32 v35, v34
	s_nop 1
	v_permlane32_swap_b32_e32 v34, v35
	v_add_f32_e32 v143, v34, v35
	v_fmamk_f32 v38, v143, 0xba000000, v21
	v_fmamk_f32 v132, v143, 0xba000000, v20
	v_fmamk_f32 v20, v143, 0xba000000, v19
	v_fmamk_f32 v39, v143, 0xba000000, v25
	v_fmamk_f32 v21, v143, 0xba000000, v23
	v_fmac_f32_e32 v22, 0xba000000, v143
	v_fmamk_f32 v29, v143, 0xba000000, v29
	v_fmamk_f32 v28, v143, 0xba000000, v28
	v_fmamk_f32 v27, v143, 0xba000000, v27
	v_fmac_f32_e32 v26, 0xba000000, v143
	v_fmac_f32_e32 v18, 0xba000000, v143
	v_fmamk_f32 v133, v143, 0xba000000, v24
	v_mov_b32_e32 v19, v22
	v_pk_mul_f32 v[24:25], v[20:21], v[20:21]
	v_pk_mul_f32 v[34:35], v[38:39], v[38:39]
	v_pk_mul_f32 v[36:37], v[28:29], v[28:29]
	v_pk_mul_f32 v[42:43], v[26:27], v[26:27]
	v_fmamk_f32 v32, v143, 0xba000000, v32
	v_fmac_f32_e32 v30, 0xba000000, v143
	v_pk_fma_f32 v[24:25], v[18:19], v[18:19], v[24:25]
	v_pk_fma_f32 v[34:35], v[132:133], v[132:133], v[34:35]
	v_pk_mov_b32 v[54:55], v[42:43], v[36:37] op_sel:[1,0]
	v_mov_b32_e32 v43, v37
	v_fmamk_f32 v33, v143, 0xba000000, v33
	v_fmamk_f32 v31, v143, 0xba000000, v31
	v_fmamk_f32 v9, v143, 0xba000000, v9
	v_fmamk_f32 v8, v143, 0xba000000, v8
	v_fmamk_f32 v7, v143, 0xba000000, v7
	v_fmac_f32_e32 v6, 0xba000000, v143
	v_mul_f32_e32 v40, v30, v30
	v_mul_f32_e32 v44, v32, v32
	v_pk_add_f32 v[24:25], v[24:25], v[34:35]
	v_pk_add_f32 v[34:35], v[54:55], v[42:43]
	v_fmamk_f32 v5, v143, 0xba000000, v5
	v_fmamk_f32 v4, v143, 0xba000000, v4
	v_fmamk_f32 v3, v143, 0xba000000, v3
	v_fmac_f32_e32 v2, 0xba000000, v143
	v_pk_mul_f32 v[46:47], v[8:9], v[8:9]
	v_pk_mul_f32 v[48:49], v[6:7], v[6:7]
	v_pk_fma_f32 v[36:37], v[30:31], v[30:31], v[40:41] op_sel_hi:[1,1,0]
	v_pk_fma_f32 v[44:45], v[32:33], v[32:33], v[44:45] op_sel_hi:[1,1,0]
	v_pk_add_f32 v[24:25], v[24:25], v[24:25] op_sel_hi:[0,1]
	v_pk_add_f32 v[34:35], v[34:35], v[34:35] op_sel_hi:[0,1]
	v_fmamk_f32 v12, v143, 0xba000000, v12
	v_fmac_f32_e32 v10, 0xba000000, v143
	v_pk_mov_b32 v[56:57], v[48:49], v[46:47] op_sel:[1,0]
	v_mov_b32_e32 v49, v47
	v_mul_f32_e32 v36, v2, v2
	v_mul_f32_e32 v44, v3, v3
	v_mul_f32_e32 v34, v4, v4
	v_mul_f32_e32 v24, v5, v5
	v_fmamk_f32 v13, v143, 0xba000000, v13
	v_fmamk_f32 v11, v143, 0xba000000, v11
	v_mul_f32_e32 v50, v10, v10
	v_mul_f32_e32 v52, v12, v12
	v_pk_add_f32 v[42:43], v[56:57], v[48:49]
	v_pk_add_f32 v[36:37], v[36:37], v[44:45]
	v_pk_add_f32 v[24:25], v[34:35], v[24:25]
	v_pk_fma_f32 v[144:145], v[10:11], v[10:11], v[50:51] op_sel_hi:[1,1,0]
	v_pk_fma_f32 v[146:147], v[12:13], v[12:13], v[52:53] op_sel_hi:[1,1,0]
	v_pk_add_f32 v[148:149], v[42:43], v[42:43] op_sel_hi:[0,1]
	v_pk_add_f32 v[24:25], v[36:37], v[24:25]
	global_load_dwordx4 v[94:97], v[106:107], off
	global_load_dwordx4 v[86:89], v[106:107], off offset:1024
	global_load_dwordx4 v[98:101], v[108:109], off
	global_load_dwordx4 v[90:93], v[108:109], off offset:1024
	global_load_dwordx4 v[78:81], v[106:107], off offset:2048
	global_load_dwordx4 v[70:73], v[106:107], off offset:3072
	global_load_dwordx4 v[82:85], v[108:109], off offset:2048
	global_load_dwordx4 v[74:77], v[108:109], off offset:3072
	global_load_dwordx4 v[62:65], v[110:111], off
	global_load_dwordx4 v[66:69], v[112:113], off
	global_load_dwordx4 v[54:57], v[114:115], off
	global_load_dwordx4 v[58:61], v[116:117], off
	global_load_dwordx4 v[46:49], v[118:119], off
	global_load_dwordx4 v[50:53], v[120:121], off
	global_load_dwordx4 v[34:37], v[122:123], off
	global_load_dwordx4 v[42:45], v[124:125], off
	v_fmamk_f32 v17, v143, 0xba000000, v17
	v_pk_add_f32 v[24:25], v[24:25], v[24:25] op_sel_hi:[0,1]
	v_fmamk_f32 v16, v143, 0xba000000, v16
	v_fmamk_f32 v15, v143, 0xba000000, v15
	v_fmac_f32_e32 v14, 0xba000000, v143
	v_mul_f32_e32 v144, v14, v14
	v_mul_f32_e32 v146, v15, v15
	v_mul_f32_e32 v148, v16, v16
	v_mul_f32_e32 v24, v17, v17
	v_pk_add_f32 v[144:145], v[144:145], v[146:147]
	v_pk_add_f32 v[24:25], v[148:149], v[24:25]
	s_nop 0
	v_pk_add_f32 v[24:25], v[144:145], v[24:25]
	s_nop 0
	v_add_f32_e32 v19, v24, v25
	s_waitcnt lgkmcnt(0)
	s_nop 1
	v_add_f32_dpp v19, v19, v19 quad_perm:[1,0,3,2] row_mask:0xf bank_mask:0xf
	s_nop 1
	v_add_f32_dpp v19, v19, v19 quad_perm:[2,3,0,1] row_mask:0xf bank_mask:0xf
	s_nop 1
	v_add_f32_dpp v19, v19, v19 row_half_mirror row_mask:0xf bank_mask:0xf
	s_nop 1
	v_add_f32_dpp v19, v19, v19 row_mirror row_mask:0xf bank_mask:0xf
	v_mov_b32_e32 v23, v19
	s_nop 1
	v_permlane16_swap_b32_e32 v19, v23
	v_add_f32_e32 v19, v19, v23
	v_mov_b32_e32 v23, v19
	s_nop 1
	v_permlane32_swap_b32_e32 v19, v23
	v_add_f32_e32 v19, v19, v23
	v_fmamk_f32 v19, v19, 0x3a000000, v105
	v_mul_f32_e32 v23, 0x4f800000, v19
	v_cmp_gt_f32_e32 vcc, s1, v19
	s_nop 1
	v_cndmask_b32_e32 v19, v19, v23, vcc
	v_sqrt_f32_e32 v23, v19
	s_nop 0
	v_add_u32_e32 v24, -1, v23
	v_add_u32_e32 v25, 1, v23
	v_fma_f32 v40, -v24, v23, v19
	v_fma_f32 v127, -v25, v23, v19
	v_cmp_ge_f32_e64 s[10:11], 0, v40
	s_nop 1
	v_cndmask_b32_e64 v23, v23, v24, s[10:11]
	v_cmp_lt_f32_e64 s[10:11], 0, v127
	s_nop 1
	v_cndmask_b32_e64 v23, v23, v25, s[10:11]
	v_mul_f32_e32 v24, 0x37800000, v23
	v_cndmask_b32_e32 v23, v23, v24, vcc
	v_cmp_class_f32_e32 vcc, v19, v140
	s_nop 1
	v_cndmask_b32_e32 v19, v23, v19, vcc
	v_div_scale_f32 v23, s[4:5], v19, v19, 1.0
	v_rcp_f32_e32 v24, v23
	s_nop 0
	v_fma_f32 v25, -v23, v24, 1.0
	v_fmac_f32_e32 v24, v25, v24
	v_div_scale_f32 v25, vcc, 1.0, v19, 1.0
	v_mul_f32_e32 v40, v25, v24
	v_fma_f32 v127, -v23, v40, v25
	v_fmac_f32_e32 v40, v127, v24
	v_fma_f32 v23, -v23, v40, v25
	v_div_fmas_f32 v23, v23, v24, v40
	v_div_fixup_f32 v40, v23, v19, 1.0
	v_ashrrev_i32_e32 v127, 31, v126
	s_and_saveexec_b64 s[4:5], s[8:9]
	s_cbranch_execz .LBB0_1964
	v_mul_f32_e32 v24, 0x3a000000, v143
	v_lshl_add_u64 v[144:145], v[126:127], 2, s[34:35]
	v_mov_b32_e32 v25, v40
	global_store_dwordx2 v[144:145], v[24:25], off

.LBB0_2372:
	s_or_b64 exec, exec, s[16:17]
	v_sub_f32_e32 v21, v21, v232
	v_sub_f32_e32 v20, v20, v232
	v_sub_f32_e32 v23, v23, v232
	v_sub_f32_e32 v22, v22, v232
	v_sub_f32_e32 v11, v11, v232
	v_sub_f32_e32 v10, v10, v232
	v_pk_mul_f32 v[22:23], v[150:151], v[22:23] op_sel_hi:[0,1]
	v_pk_mul_f32 v[20:21], v[150:151], v[20:21] op_sel_hi:[0,1]
	v_sub_f32_e32 v9, v9, v232
	v_sub_f32_e32 v8, v8, v232
	v_pk_mul_f32 v[10:11], v[150:151], v[10:11] op_sel_hi:[0,1]
	v_pk_fma_f32 v[16:17], v[12:13], v[20:21], v[16:17]
	v_pk_fma_f32 v[12:13], v[14:15], v[22:23], v[18:19]
	v_pk_mul_f32 v[14:15], v[148:149], v[172:173] op_sel_hi:[0,1]
	v_pk_mul_f32 v[18:19], v[148:149], v[170:171] op_sel_hi:[0,1]
	v_pk_mul_f32 v[8:9], v[150:151], v[8:9] op_sel_hi:[0,1]
	v_pk_fma_f32 v[2:3], v[2:3], v[10:11], v[6:7]
	v_pk_mul_f32 v[6:7], v[148:149], v[158:159] op_sel_hi:[0,1]
	v_sub_f32_e32 v33, v33, v232
	v_sub_f32_e32 v32, v32, v232
	v_sub_f32_e32 v35, v35, v232
	v_sub_f32_e32 v34, v34, v232
	v_pk_fma_f32 v[18:19], v[152:153], v[164:165], v[18:19] op_sel_hi:[0,1,1]
	v_pk_fma_f32 v[14:15], v[152:153], v[166:167], v[14:15] op_sel_hi:[0,1,1]
	v_pk_fma_f32 v[0:1], v[0:1], v[8:9], v[4:5]
	v_pk_mul_f32 v[4:5], v[148:149], v[160:161] op_sel_hi:[0,1]
	v_pk_fma_f32 v[6:7], v[152:153], v[154:155], v[6:7] op_sel_hi:[0,1,1]
	v_pk_mul_f32 v[34:35], v[150:151], v[34:35] op_sel_hi:[0,1]
	v_pk_mul_f32 v[32:33], v[150:151], v[32:33] op_sel_hi:[0,1]
	v_pk_fma_f32 v[12:13], v[12:13], s[14:15], v[14:15] op_sel_hi:[1,0,1]
	v_pk_fma_f32 v[14:15], v[16:17], s[14:15], v[18:19] op_sel_hi:[1,0,1]
	v_pk_fma_f32 v[4:5], v[152:153], v[156:157], v[4:5] op_sel_hi:[0,1,1]
	v_pk_fma_f32 v[6:7], v[0:1], s[14:15], v[6:7] op_sel_hi:[1,0,1]
	v_pk_fma_f32 v[28:29], v[24:25], v[32:33], v[28:29]
	v_pk_fma_f32 v[24:25], v[26:27], v[34:35], v[30:31]
	v_pk_mul_f32 v[26:27], v[148:149], v[184:185] op_sel_hi:[0,1]
	v_pk_mul_f32 v[30:31], v[148:149], v[182:183] op_sel_hi:[0,1]
	v_pk_fma_f32 v[4:5], v[2:3], s[14:15], v[4:5] op_sel_hi:[1,0,1]
	v_mov_b32_e32 v8, v6
	v_mov_b32_e32 v9, v14
	v_mov_b32_e32 v10, v7
	v_mov_b32_e32 v11, v15
	v_sub_f32_e32 v57, v57, v232
	v_sub_f32_e32 v56, v56, v232
	v_sub_f32_e32 v59, v59, v232
	v_sub_f32_e32 v58, v58, v232
	v_sub_f32_e32 v45, v45, v232
	v_sub_f32_e32 v44, v44, v232
	v_sub_f32_e32 v47, v47, v232
	v_sub_f32_e32 v46, v46, v232
	v_pk_fma_f32 v[30:31], v[152:153], v[178:179], v[30:31] op_sel_hi:[0,1,1]
	v_pk_fma_f32 v[26:27], v[152:153], v[180:181], v[26:27] op_sel_hi:[0,1,1]
	v_pk_add_f32 v[8:9], v[8:9], v[10:11]
	v_mov_b32_e32 v10, v4
	v_mov_b32_e32 v11, v12
	v_mov_b32_e32 v16, v5
	v_mov_b32_e32 v17, v13
	v_pk_mul_f32 v[58:59], v[150:151], v[58:59] op_sel_hi:[0,1]
	v_pk_mul_f32 v[56:57], v[150:151], v[56:57] op_sel_hi:[0,1]
	v_pk_mul_f32 v[46:47], v[150:151], v[46:47] op_sel_hi:[0,1]
	v_pk_mul_f32 v[44:45], v[150:151], v[44:45] op_sel_hi:[0,1]
	v_pk_fma_f32 v[24:25], v[24:25], s[14:15], v[26:27] op_sel_hi:[1,0,1]
	v_pk_fma_f32 v[26:27], v[28:29], s[14:15], v[30:31] op_sel_hi:[1,0,1]
	v_pk_add_f32 v[10:11], v[10:11], v[16:17]
	v_sub_f32_e32 v81, v81, v232
	v_sub_f32_e32 v80, v80, v232
	v_sub_f32_e32 v83, v83, v232
	v_sub_f32_e32 v82, v82, v232
	v_sub_f32_e32 v69, v69, v232
	v_sub_f32_e32 v68, v68, v232
	v_sub_f32_e32 v71, v71, v232
	v_sub_f32_e32 v70, v70, v232
	v_pk_fma_f32 v[52:53], v[48:49], v[56:57], v[52:53]
	v_pk_fma_f32 v[48:49], v[50:51], v[58:59], v[54:55]
	v_pk_mul_f32 v[50:51], v[148:149], v[200:201] op_sel_hi:[0,1]
	v_pk_mul_f32 v[54:55], v[148:149], v[198:199] op_sel_hi:[0,1]
	v_pk_fma_f32 v[40:41], v[36:37], v[44:45], v[40:41]
	v_pk_fma_f32 v[36:37], v[38:39], v[46:47], v[42:43]
	v_pk_mul_f32 v[38:39], v[148:149], v[192:193] op_sel_hi:[0,1]
	v_pk_mul_f32 v[42:43], v[148:149], v[190:191] op_sel_hi:[0,1]
	v_pk_add_f32 v[8:9], v[8:9], v[10:11]
	v_pk_mov_b32 v[10:11], v[26:27], v[24:25] op_sel:[1,0]
	v_mov_b32_e32 v16, v26
	v_mov_b32_e32 v17, v25
	v_pk_mul_f32 v[82:83], v[150:151], v[82:83] op_sel_hi:[0,1]
	v_pk_mul_f32 v[80:81], v[150:151], v[80:81] op_sel_hi:[0,1]
	v_pk_mul_f32 v[70:71], v[150:151], v[70:71] op_sel_hi:[0,1]
	v_pk_mul_f32 v[68:69], v[150:151], v[68:69] op_sel_hi:[0,1]
	v_pk_fma_f32 v[54:55], v[152:153], v[194:195], v[54:55] op_sel_hi:[0,1,1]
	v_pk_fma_f32 v[50:51], v[152:153], v[196:197], v[50:51] op_sel_hi:[0,1,1]
	v_pk_fma_f32 v[42:43], v[152:153], v[186:187], v[42:43] op_sel_hi:[0,1,1]
	v_pk_fma_f32 v[38:39], v[152:153], v[188:189], v[38:39] op_sel_hi:[0,1,1]
	v_pk_add_f32 v[10:11], v[10:11], v[16:17]
	v_pk_fma_f32 v[76:77], v[72:73], v[80:81], v[76:77]
	v_pk_fma_f32 v[72:73], v[74:75], v[82:83], v[78:79]
	v_pk_mul_f32 v[74:75], v[148:149], v[216:217] op_sel_hi:[0,1]
	v_pk_mul_f32 v[78:79], v[148:149], v[214:215] op_sel_hi:[0,1]
	v_pk_fma_f32 v[64:65], v[60:61], v[68:69], v[64:65]
	v_pk_fma_f32 v[60:61], v[62:63], v[70:71], v[66:67]
	v_pk_mul_f32 v[62:63], v[148:149], v[208:209] op_sel_hi:[0,1]
	v_pk_mul_f32 v[66:67], v[148:149], v[206:207] op_sel_hi:[0,1]
	v_pk_fma_f32 v[48:49], v[48:49], s[14:15], v[50:51] op_sel_hi:[1,0,1]
	v_pk_fma_f32 v[50:51], v[52:53], s[14:15], v[54:55] op_sel_hi:[1,0,1]
	v_pk_fma_f32 v[36:37], v[36:37], s[14:15], v[38:39] op_sel_hi:[1,0,1]
	v_pk_fma_f32 v[38:39], v[40:41], s[14:15], v[42:43] op_sel_hi:[1,0,1]
	v_add_f32_e32 v8, 0, v8
	v_pk_add_f32 v[10:11], v[10:11], v[10:11] op_sel:[0,1] op_sel_hi:[1,0]
	v_pk_fma_f32 v[78:79], v[152:153], v[210:211], v[78:79] op_sel_hi:[0,1,1]
	v_pk_fma_f32 v[74:75], v[152:153], v[212:213], v[74:75] op_sel_hi:[0,1,1]
	v_pk_fma_f32 v[66:67], v[152:153], v[202:203], v[66:67] op_sel_hi:[0,1,1]
	v_pk_fma_f32 v[62:63], v[152:153], v[204:205], v[62:63] op_sel_hi:[0,1,1]
	v_add_f32_e32 v8, v8, v9
	v_add_f32_e32 v16, v38, v39
	v_add_f32_e32 v18, v36, v37
	v_mov_b32_e32 v9, v50
	v_mov_b32_e32 v11, v51
	v_mov_b32_e32 v17, v48
	v_mov_b32_e32 v19, v49
	v_pk_fma_f32 v[72:73], v[72:73], s[14:15], v[74:75] op_sel_hi:[1,0,1]
	v_pk_fma_f32 v[74:75], v[76:77], s[14:15], v[78:79] op_sel_hi:[1,0,1]
	s_waitcnt vmcnt(0)
	v_sub_f32_e32 v77, v93, v232
	v_sub_f32_e32 v76, v92, v232
	v_sub_f32_e32 v79, v95, v232
	v_sub_f32_e32 v78, v94, v232
	v_pk_fma_f32 v[60:61], v[60:61], s[14:15], v[62:63] op_sel_hi:[1,0,1]
	v_pk_fma_f32 v[62:63], v[64:65], s[14:15], v[66:67] op_sel_hi:[1,0,1]
	v_pk_add_f32 v[8:9], v[8:9], v[10:11]
	v_pk_add_f32 v[10:11], v[16:17], v[18:19]
	v_pk_mul_f32 v[78:79], v[150:151], v[78:79] op_sel_hi:[0,1]
	v_pk_mul_f32 v[76:77], v[150:151], v[76:77] op_sel_hi:[0,1]
	v_pk_mul_f32 v[0:1], v[148:149], v[224:225] op_sel_hi:[0,1]
	v_pk_mul_f32 v[2:3], v[148:149], v[222:223] op_sel_hi:[0,1]
	v_pk_add_f32 v[8:9], v[8:9], v[10:11]
	v_pk_mov_b32 v[10:11], v[62:63], v[60:61] op_sel:[1,0]
	v_mov_b32_e32 v16, v62
	v_mov_b32_e32 v17, v61
	v_pk_fma_f32 v[76:77], v[84:85], v[76:77], v[88:89]
	v_pk_fma_f32 v[78:79], v[86:87], v[78:79], v[90:91]
	v_pk_fma_f32 v[2:3], v[152:153], v[218:219], v[2:3] op_sel_hi:[0,1,1]
	v_pk_fma_f32 v[0:1], v[152:153], v[220:221], v[0:1] op_sel_hi:[0,1,1]
	v_pk_add_f32 v[10:11], v[10:11], v[16:17]
	v_pk_fma_f32 v[0:1], v[78:79], s[14:15], v[0:1] op_sel_hi:[1,0,1]
	v_pk_fma_f32 v[2:3], v[76:77], s[14:15], v[2:3] op_sel_hi:[1,0,1]
	v_pk_add_f32 v[8:9], v[8:9], v[8:9] op_sel:[0,1] op_sel_hi:[1,0]
	v_pk_add_f32 v[10:11], v[10:11], v[10:11] op_sel:[0,1] op_sel_hi:[1,0]
	v_add_f32_e32 v16, v74, v75
	v_add_f32_e32 v18, v72, v73
	v_mov_b32_e32 v9, v2
	v_mov_b32_e32 v11, v3
	v_mov_b32_e32 v17, v0
	v_mov_b32_e32 v19, v1
	v_pk_add_f32 v[8:9], v[8:9], v[10:11]
	v_pk_add_f32 v[10:11], v[16:17], v[18:19]
	v_lshlrev_b64 v[154:155], 11, v[96:97]
	v_pk_add_f32 v[8:9], v[8:9], v[10:11]
	v_add_u32_e32 v96, s22, v96
	v_add_f32_e32 v8, v8, v9
	s_waitcnt lgkmcnt(0)
	s_nop 1
	v_add_f32_dpp v8, v8, v8 quad_perm:[1,0,3,2] row_mask:0xf bank_mask:0xf
	s_nop 1
	v_add_f32_dpp v8, v8, v8 quad_perm:[2,3,0,1] row_mask:0xf bank_mask:0xf
	s_nop 1
	v_add_f32_dpp v8, v8, v8 row_half_mirror row_mask:0xf bank_mask:0xf
	s_nop 1
	v_add_f32_dpp v8, v8, v8 row_mirror row_mask:0xf bank_mask:0xf
	v_mov_b32_e32 v9, v8
	s_nop 1
	v_permlane16_swap_b32_e32 v8, v9
	v_add_f32_e32 v8, v8, v9
	v_mov_b32_e32 v9, v8
	s_nop 1
	v_permlane32_swap_b32_e32 v8, v9
	v_add_f32_e32 v20, v8, v9
	v_fmamk_f32 v7, v20, 0xba000000, v7
	v_fmamk_f32 v15, v20, 0xba000000, v15
	v_fmamk_f32 v5, v20, 0xba000000, v5
	v_fmac_f32_e32 v6, 0xba000000, v20
	v_fmamk_f32 v13, v20, 0xba000000, v13
	v_fmac_f32_e32 v14, 0xba000000, v20
	v_mov_b32_e32 v10, v7
	v_mov_b32_e32 v11, v15
	v_fmac_f32_e32 v4, 0xba000000, v20
	v_fmac_f32_e32 v12, 0xba000000, v20
	v_mov_b32_e32 v8, v6
	v_mov_b32_e32 v9, v14
	v_pk_mul_f32 v[10:11], v[10:11], v[10:11]
	v_mov_b32_e32 v16, v5
	v_mov_b32_e32 v17, v13
	v_pk_fma_f32 v[8:9], v[8:9], v[8:9], v[10:11]
	v_mov_b32_e32 v10, v4
	v_mov_b32_e32 v11, v12
	v_pk_mul_f32 v[16:17], v[16:17], v[16:17]
	v_fmamk_f32 v27, v20, 0xba000000, v27
	v_pk_fma_f32 v[10:11], v[10:11], v[10:11], v[16:17]
	v_fmac_f32_e32 v26, 0xba000000, v20
	v_pk_add_f32 v[8:9], v[8:9], v[10:11]
	v_fmamk_f32 v25, v20, 0xba000000, v25
	v_fmac_f32_e32 v24, 0xba000000, v20
	v_pk_add_f32 v[8:9], v[8:9], v[8:9] op_sel_hi:[0,1]
	v_pk_mul_f32 v[10:11], v[24:25], v[24:25]
	v_pk_mul_f32 v[16:17], v[26:27], v[26:27]
	v_fmac_f32_e32 v38, 0xba000000, v20
	v_pk_mov_b32 v[18:19], v[16:17], v[10:11] op_sel:[1,0]
	v_mov_b32_e32 v17, v11
	v_fmamk_f32 v39, v20, 0xba000000, v39
	v_fmac_f32_e32 v36, 0xba000000, v20
	v_mul_f32_e32 v8, v38, v38
	v_pk_add_f32 v[10:11], v[18:19], v[16:17]
	v_fmamk_f32 v37, v20, 0xba000000, v37
	v_pk_fma_f32 v[16:17], v[38:39], v[38:39], v[8:9] op_sel_hi:[1,1,0]
	v_mul_f32_e32 v8, v36, v36
	v_pk_add_f32 v[10:11], v[10:11], v[10:11] op_sel_hi:[0,1]
	v_pk_fma_f32 v[18:19], v[36:37], v[36:37], v[8:9] op_sel_hi:[1,1,0]
	v_fmamk_f32 v49, v20, 0xba000000, v49
	v_fmac_f32_e32 v48, 0xba000000, v20
	v_fmamk_f32 v51, v20, 0xba000000, v51
	v_fmac_f32_e32 v50, 0xba000000, v20
	v_mul_f32_e32 v16, v50, v50
	v_mul_f32_e32 v18, v51, v51
	v_mul_f32_e32 v10, v48, v48
	v_mul_f32_e32 v8, v49, v49
	v_pk_add_f32 v[16:17], v[16:17], v[18:19]
	v_pk_add_f32 v[8:9], v[10:11], v[8:9]
	v_fmamk_f32 v63, v20, 0xba000000, v63
	v_pk_add_f32 v[8:9], v[16:17], v[8:9]
	v_fmac_f32_e32 v62, 0xba000000, v20
	v_fmamk_f32 v61, v20, 0xba000000, v61
	v_fmac_f32_e32 v60, 0xba000000, v20
	v_pk_add_f32 v[8:9], v[8:9], v[8:9] op_sel_hi:[0,1]
	v_pk_mul_f32 v[10:11], v[60:61], v[60:61]
	v_pk_mul_f32 v[16:17], v[62:63], v[62:63]
	v_fmac_f32_e32 v74, 0xba000000, v20
	v_pk_mov_b32 v[18:19], v[16:17], v[10:11] op_sel:[1,0]
	v_mov_b32_e32 v17, v11
	v_fmamk_f32 v75, v20, 0xba000000, v75
	v_fmac_f32_e32 v72, 0xba000000, v20
	v_mul_f32_e32 v8, v74, v74
	v_pk_add_f32 v[10:11], v[18:19], v[16:17]
	v_fmamk_f32 v73, v20, 0xba000000, v73
	v_pk_fma_f32 v[16:17], v[74:75], v[74:75], v[8:9] op_sel_hi:[1,1,0]
	v_mul_f32_e32 v8, v72, v72
	v_pk_add_f32 v[10:11], v[10:11], v[10:11] op_sel_hi:[0,1]
	v_pk_fma_f32 v[18:19], v[72:73], v[72:73], v[8:9] op_sel_hi:[1,1,0]
	v_fmamk_f32 v1, v20, 0xba000000, v1
	v_fmac_f32_e32 v0, 0xba000000, v20
	v_fmamk_f32 v3, v20, 0xba000000, v3
	v_fmac_f32_e32 v2, 0xba000000, v20
	v_mul_f32_e32 v16, v2, v2
	v_mul_f32_e32 v18, v3, v3
	v_mul_f32_e32 v10, v0, v0
	v_mul_f32_e32 v8, v1, v1
	v_pk_add_f32 v[16:17], v[16:17], v[18:19]
	v_pk_add_f32 v[8:9], v[10:11], v[8:9]
	s_nop 0
	v_pk_add_f32 v[8:9], v[16:17], v[8:9]
	s_nop 0
	v_add_f32_e32 v20, v8, v9
	ds_bpermute_b32 v21, v149, v20
	global_load_dwordx4 v[8:11], v[106:107], off
	global_load_dwordx4 v[16:19], v[108:109], off
	s_waitcnt lgkmcnt(0)
	v_add_f32_e32 v44, v20, v21
	ds_bpermute_b32 v45, v151, v44
	global_load_dwordx4 v[20:23], v[106:107], off offset:1024
	global_load_dwordx4 v[28:31], v[108:109], off offset:1024
	global_load_dwordx4 v[32:35], v[106:107], off offset:2048
	global_load_dwordx4 v[40:43], v[108:109], off offset:2048
	s_waitcnt lgkmcnt(0)
	v_add_f32_e32 v68, v44, v45
	ds_bpermute_b32 v69, v153, v68
	global_load_dwordx4 v[44:47], v[106:107], off offset:3072
	global_load_dwordx4 v[52:55], v[108:109], off offset:3072
	global_load_dwordx4 v[56:59], v[110:111], off
	global_load_dwordx4 v[64:67], v[112:113], off
	s_waitcnt lgkmcnt(0)
	v_add_f32_e32 v88, v68, v69
	ds_bpermute_b32 v89, v226, v88
	global_load_dwordx4 v[68:71], v[114:115], off
	global_load_dwordx4 v[76:79], v[116:117], off
	global_load_dwordx4 v[80:83], v[118:119], off
	global_load_dwordx4 v[84:87], v[120:121], off
	s_waitcnt lgkmcnt(0)
	v_add_f32_e32 v98, v88, v89
	global_load_dwordx4 v[88:91], v[122:123], off
	global_load_dwordx4 v[92:95], v[124:125], off
	ds_bpermute_b32 v148, v227, v98
	s_waitcnt lgkmcnt(0)
	v_add_f32_e32 v98, v98, v148
	ds_bpermute_b32 v148, v228, v98
	s_waitcnt lgkmcnt(0)
	v_add_f32_e32 v98, v98, v148
	v_fmamk_f32 v98, v98, 0x3a000000, v229
	v_mul_f32_e32 v148, 0x4f800000, v98
	v_cmp_gt_f32_e32 vcc, s28, v98
	s_nop 1
	v_cndmask_b32_e32 v98, v98, v148, vcc
	v_sqrt_f32_e32 v148, v98
	s_nop 0
	v_add_u32_e32 v150, -1, v148
	v_fma_f32 v152, -v150, v148, v98
	v_cmp_ge_f32_e64 s[0:1], 0, v152
	v_add_u32_e32 v152, 1, v148
	s_nop 0
	v_cndmask_b32_e64 v150, v148, v150, s[0:1]
	v_fma_f32 v148, -v152, v148, v98
	v_cmp_lt_f32_e64 s[0:1], 0, v148
	s_nop 1
	v_cndmask_b32_e64 v148, v150, v152, s[0:1]
	v_mul_f32_e32 v150, 0x37800000, v148
	v_cndmask_b32_e32 v148, v148, v150, vcc
	v_cmp_class_f32_e32 vcc, v98, v230
	s_nop 1
	v_cndmask_b32_e32 v98, v148, v98, vcc
	v_div_scale_f32 v148, s[0:1], v98, v98, 1.0
	v_rcp_f32_e32 v150, v148
	s_nop 0
	v_fma_f32 v97, -v148, v150, 1.0
	v_fmac_f32_e32 v150, v97, v150
	v_div_scale_f32 v97, vcc, 1.0, v98, 1.0
	v_mul_f32_e32 v152, v97, v150
	v_fma_f32 v156, -v148, v152, v97
	v_fmac_f32_e32 v152, v156, v150
	v_fma_f32 v97, -v148, v152, v97
	v_div_fmas_f32 v97, v97, v150, v152
	v_div_fixup_f32 v98, v97, v98, 1.0
	v_pk_mul_f32 v[4:5], v[4:5], v[98:99] op_sel_hi:[1,0]
	v_pk_mul_f32 v[156:157], v[6:7], v[98:99] op_sel_hi:[1,0]
	s_waitcnt vmcnt(14)
	v_pk_fma_f32 v[6:7], v[10:11], v[4:5], v[18:19]
	v_pk_mul_f32 v[10:11], v[12:13], v[98:99] op_sel_hi:[1,0]
	v_pk_mul_f32 v[12:13], v[26:27], v[98:99] op_sel_hi:[1,0]
	v_pk_mul_f32 v[0:1], v[0:1], v[98:99] op_sel_hi:[1,0]
	v_pk_fma_f32 v[4:5], v[8:9], v[156:157], v[16:17]
	v_pk_mul_f32 v[8:9], v[14:15], v[98:99] op_sel_hi:[1,0]
	s_waitcnt vmcnt(10)
	v_pk_fma_f32 v[12:13], v[32:33], v[12:13], v[40:41]
	v_pk_mul_f32 v[32:33], v[2:3], v[98:99] op_sel_hi:[1,0]
	v_pk_mul_f32 v[14:15], v[24:25], v[98:99] op_sel_hi:[1,0]
	v_pk_mul_f32 v[16:17], v[38:39], v[98:99] op_sel_hi:[1,0]
	v_pk_mul_f32 v[18:19], v[36:37], v[98:99] op_sel_hi:[1,0]
	v_pk_fma_f32 v[10:11], v[22:23], v[10:11], v[30:31]
	v_pk_fma_f32 v[8:9], v[20:21], v[8:9], v[28:29]
	v_pk_fma_f32 v[14:15], v[34:35], v[14:15], v[42:43]
	s_waitcnt vmcnt(8)
	v_pk_fma_f32 v[18:19], v[46:47], v[18:19], v[54:55]
	v_pk_fma_f32 v[16:17], v[44:45], v[16:17], v[52:53]
	v_pk_mul_f32 v[20:21], v[50:51], v[98:99] op_sel_hi:[1,0]
	v_pk_mul_f32 v[22:23], v[48:49], v[98:99] op_sel_hi:[1,0]
	s_waitcnt vmcnt(6)
	v_pk_fma_f32 v[20:21], v[56:57], v[20:21], v[64:65]
	v_pk_fma_f32 v[22:23], v[58:59], v[22:23], v[66:67]
	v_pk_mul_f32 v[24:25], v[62:63], v[98:99] op_sel_hi:[1,0]
	v_pk_mul_f32 v[26:27], v[60:61], v[98:99] op_sel_hi:[1,0]
	s_waitcnt vmcnt(0)
	v_pk_fma_f32 v[2:3], v[90:91], v[0:1], v[94:95]
	v_pk_fma_f32 v[0:1], v[88:89], v[32:33], v[92:93]
	v_lshl_add_u64 v[32:33], v[154:155], 2, v[144:145]
	global_store_dwordx4 v[32:33], v[4:7], off
	global_store_dwordx4 v[32:33], v[8:11], off offset:1024
	global_store_dwordx4 v[32:33], v[12:15], off offset:2048
	global_store_dwordx4 v[32:33], v[16:19], off offset:3072
	v_add_co_u32_e32 v4, vcc, s27, v32
	v_pk_mul_f32 v[28:29], v[74:75], v[98:99] op_sel_hi:[1,0]
	s_nop 0
	v_addc_co_u32_e32 v5, vcc, 0, v33, vcc
	v_cmp_lt_i32_e32 vcc, s29, v96
	v_pk_mul_f32 v[30:31], v[72:73], v[98:99] op_sel_hi:[1,0]
	s_or_b64 s[12:13], vcc, s[12:13]
	v_pk_fma_f32 v[26:27], v[70:71], v[26:27], v[78:79]
	v_pk_fma_f32 v[24:25], v[68:69], v[24:25], v[76:77]
	v_pk_fma_f32 v[30:31], v[82:83], v[30:31], v[86:87]
	v_pk_fma_f32 v[28:29], v[80:81], v[28:29], v[84:85]
	global_store_dwordx4 v[4:5], v[20:23], off
	global_store_dwordx4 v[4:5], v[24:27], off offset:1024
	global_store_dwordx4 v[4:5], v[28:31], off offset:2048
	global_store_dwordx4 v[4:5], v[0:3], off offset:3072
	s_andn2_b64 exec, exec, s[12:13]
	s_cbranch_execz .LBB0_2451
